# v32
# speedup vs baseline: 1.0085x; 1.0085x over previous
.LBB0_106:
	s_cmpk_gt_i32 s23, 0x3fff
	v_mbcnt_lo_u32_b32 v186, -1, 0
	s_cbranch_scc1 .LBB0_109
	v_mbcnt_hi_u32_b32 v3, -1, v186
	v_and_b32_e32 v4, 64, v3
	v_add_u32_e32 v4, 64, v4
	v_xor_b32_e32 v5, 1, v3
	v_cmp_lt_i32_e32 vcc, v5, v4
	s_ashr_i32 s4, s24, 31
	s_ashr_i32 s5, s76, 31
	v_cndmask_b32_e32 v5, v3, v5, vcc
	v_lshlrev_b32_e32 v6, 2, v5
	v_xor_b32_e32 v5, 2, v3
	v_cmp_lt_i32_e32 vcc, v5, v4
	s_add_u32 s8, s24, s76
	s_addc_u32 s9, s4, s5
	v_cndmask_b32_e32 v5, v3, v5, vcc
	v_lshlrev_b32_e32 v7, 2, v5
	v_xor_b32_e32 v5, 4, v3
	v_cmp_lt_i32_e32 vcc, v5, v4
	s_lshl_b64 s[4:5], s[8:9], 11
	s_add_u32 s4, s14, s4
	v_cndmask_b32_e32 v5, v3, v5, vcc
	v_lshlrev_b32_e32 v8, 2, v5
	v_xor_b32_e32 v5, 8, v3
	v_cmp_lt_i32_e32 vcc, v5, v4
	s_addc_u32 s5, s15, s5
	s_ashr_i32 s35, s34, 31
	v_cndmask_b32_e32 v5, v3, v5, vcc
	v_lshlrev_b32_e32 v9, 2, v5
	v_xor_b32_e32 v5, 16, v3
	v_cmp_lt_i32_e32 vcc, v5, v4
	s_lshl_b64 s[8:9], s[8:9], 12
	v_mov_b32_e32 v12, 0x358637bd
	v_cndmask_b32_e32 v5, v3, v5, vcc
	v_lshlrev_b32_e32 v10, 2, v5
	v_xor_b32_e32 v5, 32, v3
	v_cmp_lt_i32_e32 vcc, v5, v4
	s_mov_b32 s10, 0x800000
	s_nop 0
	v_cndmask_b32_e32 v3, v3, v5, vcc
	v_lshlrev_b32_e32 v11, 2, v3
	v_mov_b32_e32 v3, 0
	v_lshl_add_u64 v[4:5], s[4:5], 0, v[2:3]
	s_mov_b64 s[4:5], 0x3800400
	v_lshl_add_u64 v[4:5], v[4:5], 0, s[4:5]
	s_lshl_b64 s[4:5], s[34:35], 11
	s_add_u32 s8, s52, s8
	v_lshlrev_b32_e32 v2, 4, v44
	s_addc_u32 s9, s53, s9
	v_lshl_add_u64 v[2:3], s[8:9], 0, v[2:3]
	s_mov_b64 s[8:9], 0xc00
	v_lshl_add_u64 v[2:3], v[2:3], 0, s[8:9]
	s_lshl_b64 s[8:9], s[34:35], 12
	global_load_dwordx4 v[14:17], v[2:3], off offset:-3072
	global_load_dwordx4 v[18:21], v[2:3], off offset:-2048
	global_load_dwordx4 v[22:25], v[2:3], off offset:-1024
	global_load_dwordx4 v[26:29], v[2:3], off
	v_lshl_add_u64 v[2:3], v[2:3], 0, s[8:9]
	s_waitcnt vmcnt(0)
.LBB0_108:
	s_add_i32 s23, s23, s34
	s_cmpk_gt_i32 s23, 0x3fff
	s_cbranch_scc1 .Lxn_nopf
	global_load_dwordx4 v[48:51], v[2:3], off offset:-3072
	global_load_dwordx4 v[52:55], v[2:3], off offset:-2048
	global_load_dwordx4 v[56:59], v[2:3], off offset:-1024
	global_load_dwordx4 v[60:63], v[2:3], off
	v_lshl_add_u64 v[2:3], v[2:3], 0, s[8:9]
.Lxn_nopf:
	v_pk_mul_f32 v[30:31], v[16:17], v[16:17]
	v_pk_mul_f32 v[32:33], v[14:15], v[14:15]
	v_pk_mul_f32 v[34:35], v[20:21], v[20:21]
	v_pk_mul_f32 v[36:37], v[18:19], v[18:19]
	v_pk_mov_b32 v[44:45], v[32:33], v[30:31] op_sel:[1,0]
	v_mov_b32_e32 v33, v31
	v_pk_mov_b32 v[30:31], v[36:37], v[34:35] op_sel:[1,0]
	v_mov_b32_e32 v37, v35
	v_mul_f32_e32 v41, v27, v27
	v_mul_f32_e32 v38, v23, v23
	v_mul_f32_e32 v40, v25, v25
	v_pk_add_f32 v[32:33], v[44:45], v[32:33]
	v_pk_add_f32 v[30:31], v[30:31], v[36:37]
	v_mul_f32_e32 v13, v26, v26
	v_mul_f32_e32 v46, v28, v28
	v_mul_f32_e32 v47, v29, v29
	v_pk_fma_f32 v[34:35], v[22:23], v[22:23], v[38:39] op_sel_hi:[1,1,0]
	v_pk_fma_f32 v[38:39], v[24:25], v[24:25], v[40:41] op_sel_hi:[1,1,0]
	v_pk_add_f32 v[32:33], v[32:33], v[32:33] op_sel:[0,1] op_sel_hi:[1,0]
	v_pk_add_f32 v[30:31], v[30:31], v[30:31] op_sel:[0,1] op_sel_hi:[1,0]
	v_mov_b32_e32 v35, v46
	v_mov_b32_e32 v39, v47
	v_mov_b32_e32 v33, v13
	v_mov_b32_e32 v31, v41
	v_pk_add_f32 v[34:35], v[34:35], v[38:39]
	v_pk_add_f32 v[30:31], v[32:33], v[30:31]
	s_nop 0
	v_pk_add_f32 v[30:31], v[30:31], v[34:35]
	s_nop 0
	v_add_f32_e32 v13, v30, v31
	ds_bpermute_b32 v30, v6, v13
	s_waitcnt lgkmcnt(0)
	v_add_f32_e32 v13, v13, v30
	ds_bpermute_b32 v30, v7, v13
	s_waitcnt lgkmcnt(0)
	v_add_f32_e32 v13, v13, v30
	ds_bpermute_b32 v30, v8, v13
	s_waitcnt lgkmcnt(0)
	v_add_f32_e32 v13, v13, v30
	ds_bpermute_b32 v30, v9, v13
	s_waitcnt lgkmcnt(0)
	v_add_f32_e32 v13, v13, v30
	ds_bpermute_b32 v30, v10, v13
	s_waitcnt lgkmcnt(0)
	v_add_f32_e32 v13, v13, v30
	ds_bpermute_b32 v30, v11, v13
	s_waitcnt lgkmcnt(0)
	v_add_f32_e32 v13, v13, v30
	v_fmamk_f32 v13, v13, 0x3a800000, v12
	v_mul_f32_e32 v30, 0x4b800000, v13
	v_cmp_gt_f32_e32 vcc, s10, v13
	s_nop 1
	v_cndmask_b32_e32 v13, v13, v30, vcc
	v_rsq_f32_e32 v13, v13
	s_nop 0
	v_mul_f32_e32 v30, 0x45800000, v13
	v_cndmask_b32_e32 v30, v13, v30, vcc
	v_pk_mul_f32 v[14:15], v[30:31], v[14:15] op_sel_hi:[0,1]
	v_pk_mul_f32 v[16:17], v[30:31], v[16:17] op_sel_hi:[0,1]
	v_cvt_pk_bf16_f32 v14, v14, v15
	v_cvt_pk_bf16_f32 v15, v16, v17
	v_pk_mul_f32 v[20:21], v[30:31], v[20:21] op_sel_hi:[0,1]
	v_pk_mul_f32 v[18:19], v[30:31], v[18:19] op_sel_hi:[0,1]
	global_store_dwordx2 v[4:5], v[14:15], off offset:-1024
	v_cvt_pk_bf16_f32 v14, v18, v19
	v_cvt_pk_bf16_f32 v15, v20, v21
	v_pk_mul_f32 v[24:25], v[30:31], v[24:25] op_sel_hi:[0,1]
	v_pk_mul_f32 v[22:23], v[30:31], v[22:23] op_sel_hi:[0,1]
	global_store_dwordx2 v[4:5], v[14:15], off offset:-512
	v_cvt_pk_bf16_f32 v14, v22, v23
	v_cvt_pk_bf16_f32 v15, v24, v25
	v_pk_mul_f32 v[28:29], v[30:31], v[28:29] op_sel_hi:[0,1]
	v_pk_mul_f32 v[26:27], v[30:31], v[26:27] op_sel_hi:[0,1]
	global_store_dwordx2 v[4:5], v[14:15], off
	v_cvt_pk_bf16_f32 v14, v26, v27
	v_cvt_pk_bf16_f32 v15, v28, v29
	global_store_dwordx2 v[4:5], v[14:15], off offset:512
	v_lshl_add_u64 v[4:5], v[4:5], 0, s[4:5]
	s_cbranch_scc1 .LBB0_109
	s_waitcnt vmcnt(4)
	v_mov_b64_e32 v[14:15], v[48:49]
	v_mov_b64_e32 v[16:17], v[50:51]
	v_mov_b64_e32 v[18:19], v[52:53]
	v_mov_b64_e32 v[20:21], v[54:55]
	v_mov_b64_e32 v[22:23], v[56:57]
	v_mov_b64_e32 v[24:25], v[58:59]
	v_mov_b64_e32 v[26:27], v[60:61]
	v_mov_b64_e32 v[28:29], v[62:63]
	s_branch .LBB0_108

.LBB0_1529:
	s_or_b64 exec, exec, s[4:5]
	s_waitcnt lgkmcnt(0)
	v_mov_b32_e32 v0, 0
	s_barrier
	s_nop 0
	v_mbcnt_lo_u32_b32 v0, -1, v0
	v_mbcnt_hi_u32_b32 v0, -1, v0
	v_add_u32_e32 v0, s33, v0
	s_load_dwordx8 s[4:11], s[0:1], 0x80
	v_and_b32_e32 v1, 63, v0
	v_lshlrev_b32_e32 v2, 2, v1
	s_waitcnt lgkmcnt(0)
	global_load_dword v3, v2, s[4:5]
	global_load_dword v4, v2, s[6:7]
	global_load_dword v5, v2, s[8:9]
	global_load_dword v6, v2, s[10:11]
	v_mbcnt_hi_u32_b32 v2, -1, v186
	v_and_b32_e32 v7, 64, v2
	v_xor_b32_e32 v8, 1, v2
	v_add_u32_e32 v7, 64, v7
	v_cmp_lt_i32_e32 vcc, v8, v7
	v_xor_b32_e32 v9, 2, v2
	v_xor_b32_e32 v12, 4, v2
	v_cndmask_b32_e32 v8, v2, v8, vcc
	v_lshlrev_b32_e32 v10, 2, v8
	v_cmp_lt_i32_e32 vcc, v9, v7
	v_xor_b32_e32 v13, 8, v2
	v_xor_b32_e32 v14, 16, v2
	v_cndmask_b32_e32 v9, v2, v9, vcc
	v_cmp_lt_i32_e32 vcc, v12, v7
	v_xor_b32_e32 v15, 32, v2
	v_readfirstlane_b32 s4, v0
	s_ashr_i32 s4, s4, 6
	s_add_i32 s4, s4, s76
	s_cmpk_gt_i32 s4, 0x3fff
	s_waitcnt vmcnt(2)
	v_mul_f32_e32 v8, v3, v4
	ds_bpermute_b32 v8, v10, v8
	s_waitcnt vmcnt(0)
	v_mul_f32_e32 v11, v5, v6
	ds_bpermute_b32 v16, v10, v11
	v_lshlrev_b32_e32 v11, 2, v9
	s_waitcnt lgkmcnt(1)
	v_fmac_f32_e32 v8, v3, v4
	ds_bpermute_b32 v3, v11, v8
	s_waitcnt lgkmcnt(1)
	v_fmac_f32_e32 v16, v5, v6
	ds_bpermute_b32 v4, v11, v16
	v_cndmask_b32_e32 v5, v2, v12, vcc
	v_lshlrev_b32_e32 v12, 2, v5
	s_waitcnt lgkmcnt(1)
	v_add_f32_e32 v3, v8, v3
	ds_bpermute_b32 v5, v12, v3
	s_waitcnt lgkmcnt(1)
	v_add_f32_e32 v4, v16, v4
	ds_bpermute_b32 v6, v12, v4
	v_cmp_lt_i32_e32 vcc, v13, v7
	s_waitcnt lgkmcnt(1)
	v_add_f32_e32 v3, v3, v5
	v_cndmask_b32_e32 v8, v2, v13, vcc
	v_lshlrev_b32_e32 v13, 2, v8
	s_waitcnt lgkmcnt(0)
	v_add_f32_e32 v4, v4, v6
	ds_bpermute_b32 v5, v13, v3
	ds_bpermute_b32 v6, v13, v4
	v_cmp_lt_i32_e32 vcc, v14, v7
	s_waitcnt lgkmcnt(1)
	v_add_f32_e32 v3, v3, v5
	v_cndmask_b32_e32 v8, v2, v14, vcc
	v_lshlrev_b32_e32 v149, 2, v8
	s_waitcnt lgkmcnt(0)
	v_add_f32_e32 v5, v4, v6
	ds_bpermute_b32 v4, v149, v3
	ds_bpermute_b32 v6, v149, v5
	v_cmp_lt_i32_e32 vcc, v15, v7
	v_mov_b32_e32 v14, 0
	s_waitcnt lgkmcnt(1)
	v_add_f32_e32 v4, v3, v4
	v_cndmask_b32_e32 v2, v2, v15, vcc
	v_lshlrev_b32_e32 v153, 2, v2
	s_waitcnt lgkmcnt(0)
	v_add_f32_e32 v2, v5, v6
	ds_bpermute_b32 v5, v153, v4
	ds_bpermute_b32 v3, v153, v2
	s_cbranch_scc1 .LBB0_1532
	s_load_dwordx2 s[6:7], s[0:1], 0xa0
	v_lshlrev_b32_e32 v6, 4, v0
	v_and_b32_e32 v6, 0x1f0, v6
	s_waitcnt lgkmcnt(0)
	v_add_f32_e32 v4, v4, v5
	s_mov_b32 s11, 0x3fb8aa3b
	global_load_dwordx4 v[16:19], v6, s[6:7]
	v_add_f32_e32 v6, v2, v3
	v_mul_f32_e32 v7, 0x3fb8aa3b, v4
	v_mul_f32_e32 v8, 0x3fb8aa3b, v6
	v_fma_f32 v9, v4, s11, -v7
	v_rndne_f32_e32 v20, v7
	v_fma_f32 v21, v6, s11, -v8
	v_rndne_f32_e32 v22, v8
	v_fmac_f32_e32 v9, 0x32a5705f, v4
	v_sub_f32_e32 v7, v7, v20
	v_fmac_f32_e32 v21, 0x32a5705f, v6
	v_sub_f32_e32 v8, v8, v22
	v_add_f32_e32 v7, v7, v9
	v_cvt_i32_f32_e32 v20, v20
	v_add_f32_e32 v8, v8, v21
	v_exp_f32_e32 v7, v7
	v_cvt_i32_f32_e32 v22, v22
	v_exp_f32_e32 v8, v8
	s_mov_b32 s24, 0xc2ce8ed0
	v_ldexp_f32 v7, v7, v20
	v_cmp_ngt_f32_e32 vcc, s24, v4
	s_mov_b32 s25, 0x42b17218
	v_ldexp_f32 v8, v8, v22
	v_cndmask_b32_e32 v7, 0, v7, vcc
	v_cmp_ngt_f32_e32 vcc, s24, v6
	v_mov_b32_e32 v5, 0x7f800000
	v_lshlrev_b32_e32 v1, 3, v1
	v_cndmask_b32_e32 v8, 0, v8, vcc
	v_cmp_nlt_f32_e32 vcc, s25, v4
	s_ashr_i32 s5, s4, 31
	v_and_b32_e32 v2, 32, v0
	v_lshlrev_b32_e32 v0, 3, v0
	v_cndmask_b32_e32 v4, v5, v7, vcc
	v_cmp_nlt_f32_e32 vcc, s25, v6
	v_and_b32_e32 v3, 0x100, v1
	s_lshl_b64 s[20:21], s[4:5], 12
	v_lshlrev_b32_e32 v1, 4, v2
	v_and_b32_e32 v2, 0xf8, v0
	s_lshl_b64 s[22:23], s[4:5], 11
	v_cndmask_b32_e32 v5, v5, v8, vcc
	v_or3_b32 v0, s20, v1, v2
	v_mov_b32_e32 v1, s21
	v_or3_b32 v2, s22, v3, v2
	v_mov_b32_e32 v3, s23
	v_sub_f32_e32 v4, v4, v5
	s_mov_b32 s10, 0x3f24fd5c
	s_mov_b64 s[12:13], 0xb900800
	s_ashr_i32 s35, s34, 31
	s_mov_b64 s[18:19], 0x5800400
	v_lshl_add_u64 v[0:1], s[14:15], 0, v[0:1]
	v_lshl_add_u64 v[2:3], s[14:15], 0, v[2:3]
	v_add_f32_e32 v4, 0x3eb60549, v4
	v_mov_b32_e32 v15, 0x358637bd
	s_lshl_b64 s[6:7], s[34:35], 12
	s_lshl_b64 s[8:9], s[34:35], 11
	v_lshl_add_u64 v[0:1], v[0:1], 0, s[12:13]
	v_lshl_add_u64 v[2:3], v[2:3], 0, s[18:19]
	v_mov_b32_e32 v5, v4
	s_mov_b32 s5, 0x800000
	s_waitcnt vmcnt(0)
	v_pk_mul_f32 v[6:7], v[18:19], s[10:11] op_sel_hi:[1,0]
	v_pk_mul_f32 v[8:9], v[16:17], s[10:11] op_sel_hi:[1,0]
	global_load_dwordx2 v[24:25], v[0:1], off offset:-2048
	global_load_dwordx2 v[26:27], v[0:1], off offset:-1792
	global_load_dwordx2 v[28:29], v[0:1], off offset:-1024
	global_load_dwordx2 v[30:31], v[0:1], off offset:-768
	global_load_dwordx2 v[32:33], v[0:1], off
	global_load_dwordx2 v[34:35], v[0:1], off offset:256
	global_load_dwordx2 v[36:37], v[0:1], off offset:1024
	global_load_dwordx2 v[38:39], v[0:1], off offset:1280
	v_lshl_add_u64 v[0:1], v[0:1], 0, s[6:7]
	s_waitcnt vmcnt(0)
.LBB0_1531:
	s_add_i32 s4, s4, s34
	s_cmpk_lt_i32 s4, 0x4000
	s_cbranch_scc0 .Lcb_nopf
	global_load_dwordx2 v[40:41], v[0:1], off offset:-2048
	global_load_dwordx2 v[42:43], v[0:1], off offset:-1792
	global_load_dwordx2 v[44:45], v[0:1], off offset:-1024
	global_load_dwordx2 v[46:47], v[0:1], off offset:-768
	global_load_dwordx2 v[48:49], v[0:1], off
	global_load_dwordx2 v[50:51], v[0:1], off offset:256
	global_load_dwordx2 v[52:53], v[0:1], off offset:1024
	global_load_dwordx2 v[54:55], v[0:1], off offset:1280
	v_lshl_add_u64 v[0:1], v[0:1], 0, s[6:7]
.Lcb_nopf:
	v_mov_b64_e32 v[16:17], v[24:25]
	v_mov_b64_e32 v[18:19], v[26:27]
	v_lshlrev_b32_e32 v20, 16, v16
	v_and_b32_e32 v21, 0xffff0000, v16
	v_lshlrev_b32_e32 v22, 16, v18
	v_and_b32_e32 v23, 0xffff0000, v18
	v_lshlrev_b32_e32 v16, 16, v17
	v_and_b32_e32 v17, 0xffff0000, v17
	v_lshlrev_b32_e32 v18, 16, v19
	v_and_b32_e32 v19, 0xffff0000, v19
	v_pk_fma_f32 v[20:21], v[4:5], v[22:23], v[20:21] neg_lo:[1,0,0] neg_hi:[1,0,0]
	v_pk_fma_f32 v[16:17], v[4:5], v[18:19], v[16:17] neg_lo:[1,0,0] neg_hi:[1,0,0]
	v_mov_b32_e32 v22, v21
	v_mov_b32_e32 v23, v17
	v_mov_b32_e32 v18, v20
	v_mov_b32_e32 v19, v16
	v_pk_mul_f32 v[22:23], v[22:23], v[22:23]
	s_nop 0
	v_pk_fma_f32 v[18:19], v[18:19], v[18:19], v[22:23]
	s_nop 0
	v_add_f32_e32 v18, v18, v19
	ds_bpermute_b32 v19, v10, v18
	s_waitcnt lgkmcnt(0)
	v_add_f32_e32 v18, v18, v19
	ds_bpermute_b32 v19, v11, v18
	s_waitcnt lgkmcnt(0)
	v_add_f32_e32 v18, v18, v19
	ds_bpermute_b32 v19, v12, v18
	s_waitcnt lgkmcnt(0)
	v_add_f32_e32 v18, v18, v19
	ds_bpermute_b32 v19, v13, v18
	s_waitcnt lgkmcnt(0)
	v_add_f32_e32 v18, v18, v19
	ds_bpermute_b32 v19, v149, v18
	s_waitcnt lgkmcnt(0)
	v_add_f32_e32 v18, v18, v19
	v_fmamk_f32 v18, v18, 0x3c000000, v15
	v_mul_f32_e32 v19, 0x4b800000, v18
	v_cmp_gt_f32_e32 vcc, s5, v18
	s_nop 1
	v_cndmask_b32_e32 v18, v18, v19, vcc
	v_rsq_f32_e32 v18, v18
	s_nop 0
	v_mul_f32_e32 v19, 0x45800000, v18
	v_cndmask_b32_e32 v18, v18, v19, vcc
	v_pk_mul_f32 v[20:21], v[20:21], v[18:19] op_sel_hi:[1,0]
	v_pk_mul_f32 v[16:17], v[16:17], v[18:19] op_sel_hi:[1,0]
	v_pk_mul_f32 v[18:19], v[8:9], v[20:21]
	v_pk_mul_f32 v[16:17], v[6:7], v[16:17]
	v_cvt_pk_bf16_f32 v18, v18, v19
	s_nop 0
	v_cvt_pk_bf16_f32 v19, v16, v17
	global_store_dwordx2 v[2:3], v[18:19], off offset:-1024
	v_mov_b64_e32 v[16:17], v[28:29]
	v_mov_b64_e32 v[18:19], v[30:31]
	v_lshlrev_b32_e32 v20, 16, v16
	v_and_b32_e32 v21, 0xffff0000, v16
	v_lshlrev_b32_e32 v22, 16, v18
	v_and_b32_e32 v23, 0xffff0000, v18
	v_lshlrev_b32_e32 v16, 16, v17
	v_and_b32_e32 v17, 0xffff0000, v17
	v_lshlrev_b32_e32 v18, 16, v19
	v_and_b32_e32 v19, 0xffff0000, v19
	v_pk_fma_f32 v[20:21], v[4:5], v[22:23], v[20:21] neg_lo:[1,0,0] neg_hi:[1,0,0]
	v_pk_fma_f32 v[16:17], v[4:5], v[18:19], v[16:17] neg_lo:[1,0,0] neg_hi:[1,0,0]
	v_mov_b32_e32 v22, v21
	v_mov_b32_e32 v23, v17
	v_mov_b32_e32 v18, v20
	v_mov_b32_e32 v19, v16
	v_pk_mul_f32 v[22:23], v[22:23], v[22:23]
	s_nop 0
	v_pk_fma_f32 v[18:19], v[18:19], v[18:19], v[22:23]
	s_nop 0
	v_add_f32_e32 v18, v18, v19
	ds_bpermute_b32 v19, v10, v18
	s_waitcnt lgkmcnt(0)
	v_add_f32_e32 v18, v18, v19
	ds_bpermute_b32 v19, v11, v18
	s_waitcnt lgkmcnt(0)
	v_add_f32_e32 v18, v18, v19
	ds_bpermute_b32 v19, v12, v18
	s_waitcnt lgkmcnt(0)
	v_add_f32_e32 v18, v18, v19
	ds_bpermute_b32 v19, v13, v18
	s_waitcnt lgkmcnt(0)
	v_add_f32_e32 v18, v18, v19
	ds_bpermute_b32 v19, v149, v18
	s_waitcnt lgkmcnt(0)
	v_add_f32_e32 v18, v18, v19
	v_fmamk_f32 v18, v18, 0x3c000000, v15
	v_mul_f32_e32 v19, 0x4b800000, v18
	v_cmp_gt_f32_e32 vcc, s5, v18
	s_nop 1
	v_cndmask_b32_e32 v18, v18, v19, vcc
	v_rsq_f32_e32 v18, v18
	s_nop 0
	v_mul_f32_e32 v19, 0x45800000, v18
	v_cndmask_b32_e32 v18, v18, v19, vcc
	v_pk_mul_f32 v[20:21], v[20:21], v[18:19] op_sel_hi:[1,0]
	v_pk_mul_f32 v[16:17], v[16:17], v[18:19] op_sel_hi:[1,0]
	v_pk_mul_f32 v[18:19], v[8:9], v[20:21]
	v_pk_mul_f32 v[16:17], v[6:7], v[16:17]
	v_cvt_pk_bf16_f32 v18, v18, v19
	s_nop 0
	v_cvt_pk_bf16_f32 v19, v16, v17
	global_store_dwordx2 v[2:3], v[18:19], off offset:-512
	v_mov_b64_e32 v[16:17], v[32:33]
	v_mov_b64_e32 v[18:19], v[34:35]
	v_lshlrev_b32_e32 v20, 16, v16
	v_and_b32_e32 v21, 0xffff0000, v16
	v_lshlrev_b32_e32 v22, 16, v18
	v_and_b32_e32 v23, 0xffff0000, v18
	v_lshlrev_b32_e32 v16, 16, v17
	v_and_b32_e32 v17, 0xffff0000, v17
	v_lshlrev_b32_e32 v18, 16, v19
	v_and_b32_e32 v19, 0xffff0000, v19
	v_pk_fma_f32 v[20:21], v[4:5], v[22:23], v[20:21] neg_lo:[1,0,0] neg_hi:[1,0,0]
	v_pk_fma_f32 v[16:17], v[4:5], v[18:19], v[16:17] neg_lo:[1,0,0] neg_hi:[1,0,0]
	v_mov_b32_e32 v22, v21
	v_mov_b32_e32 v23, v17
	v_mov_b32_e32 v18, v20
	v_mov_b32_e32 v19, v16
	v_pk_mul_f32 v[22:23], v[22:23], v[22:23]
	s_nop 0
	v_pk_fma_f32 v[18:19], v[18:19], v[18:19], v[22:23]
	s_nop 0
	v_add_f32_e32 v18, v18, v19
	ds_bpermute_b32 v19, v10, v18
	s_waitcnt lgkmcnt(0)
	v_add_f32_e32 v18, v18, v19
	ds_bpermute_b32 v19, v11, v18
	s_waitcnt lgkmcnt(0)
	v_add_f32_e32 v18, v18, v19
	ds_bpermute_b32 v19, v12, v18
	s_waitcnt lgkmcnt(0)
	v_add_f32_e32 v18, v18, v19
	ds_bpermute_b32 v19, v13, v18
	s_waitcnt lgkmcnt(0)
	v_add_f32_e32 v18, v18, v19
	ds_bpermute_b32 v19, v149, v18
	s_waitcnt lgkmcnt(0)
	v_add_f32_e32 v18, v18, v19
	v_fmamk_f32 v18, v18, 0x3c000000, v15
	v_mul_f32_e32 v19, 0x4b800000, v18
	v_cmp_gt_f32_e32 vcc, s5, v18
	s_nop 1
	v_cndmask_b32_e32 v18, v18, v19, vcc
	v_rsq_f32_e32 v18, v18
	s_nop 0
	v_mul_f32_e32 v19, 0x45800000, v18
	v_cndmask_b32_e32 v18, v18, v19, vcc
	v_pk_mul_f32 v[20:21], v[20:21], v[18:19] op_sel_hi:[1,0]
	v_pk_mul_f32 v[16:17], v[16:17], v[18:19] op_sel_hi:[1,0]
	v_pk_mul_f32 v[18:19], v[8:9], v[20:21]
	v_pk_mul_f32 v[16:17], v[6:7], v[16:17]
	v_cvt_pk_bf16_f32 v18, v18, v19
	s_nop 0
	v_cvt_pk_bf16_f32 v19, v16, v17
	global_store_dwordx2 v[2:3], v[18:19], off
	v_mov_b64_e32 v[16:17], v[36:37]
	v_mov_b64_e32 v[18:19], v[38:39]
	v_lshlrev_b32_e32 v20, 16, v16
	v_and_b32_e32 v21, 0xffff0000, v16
	v_lshlrev_b32_e32 v22, 16, v18
	v_and_b32_e32 v23, 0xffff0000, v18
	v_lshlrev_b32_e32 v16, 16, v17
	v_and_b32_e32 v17, 0xffff0000, v17
	v_lshlrev_b32_e32 v18, 16, v19
	v_and_b32_e32 v19, 0xffff0000, v19
	v_pk_fma_f32 v[20:21], v[4:5], v[22:23], v[20:21] neg_lo:[1,0,0] neg_hi:[1,0,0]
	v_pk_fma_f32 v[16:17], v[4:5], v[18:19], v[16:17] neg_lo:[1,0,0] neg_hi:[1,0,0]
	v_mov_b32_e32 v22, v21
	v_mov_b32_e32 v23, v17
	v_mov_b32_e32 v18, v20
	v_mov_b32_e32 v19, v16
	v_pk_mul_f32 v[22:23], v[22:23], v[22:23]
	s_nop 0
	v_pk_fma_f32 v[18:19], v[18:19], v[18:19], v[22:23]
	s_nop 0
	v_add_f32_e32 v18, v18, v19
	ds_bpermute_b32 v19, v10, v18
	s_waitcnt lgkmcnt(0)
	v_add_f32_e32 v18, v18, v19
	ds_bpermute_b32 v19, v11, v18
	s_waitcnt lgkmcnt(0)
	v_add_f32_e32 v18, v18, v19
	ds_bpermute_b32 v19, v12, v18
	s_waitcnt lgkmcnt(0)
	v_add_f32_e32 v18, v18, v19
	ds_bpermute_b32 v19, v13, v18
	s_waitcnt lgkmcnt(0)
	v_add_f32_e32 v18, v18, v19
	ds_bpermute_b32 v19, v149, v18
	s_waitcnt lgkmcnt(0)
	v_add_f32_e32 v18, v18, v19
	v_fmamk_f32 v18, v18, 0x3c000000, v15
	v_mul_f32_e32 v19, 0x4b800000, v18
	v_cmp_gt_f32_e32 vcc, s5, v18
	s_nop 1
	v_cndmask_b32_e32 v18, v18, v19, vcc
	v_rsq_f32_e32 v18, v18
	s_nop 0
	v_mul_f32_e32 v19, 0x45800000, v18
	v_cndmask_b32_e32 v18, v18, v19, vcc
	v_pk_mul_f32 v[20:21], v[20:21], v[18:19] op_sel_hi:[1,0]
	v_pk_mul_f32 v[16:17], v[16:17], v[18:19] op_sel_hi:[1,0]
	v_pk_mul_f32 v[18:19], v[8:9], v[20:21]
	v_pk_mul_f32 v[16:17], v[6:7], v[16:17]
	v_cvt_pk_bf16_f32 v18, v18, v19
	s_nop 0
	v_cvt_pk_bf16_f32 v19, v16, v17
	global_store_dwordx2 v[2:3], v[18:19], off offset:512
	v_lshl_add_u64 v[2:3], v[2:3], 0, s[8:9]
	s_cbranch_scc0 .Lcb_done
	s_waitcnt vmcnt(4)
	v_mov_b64_e32 v[24:25], v[40:41]
	v_mov_b64_e32 v[26:27], v[42:43]
	v_mov_b64_e32 v[28:29], v[44:45]
	v_mov_b64_e32 v[30:31], v[46:47]
	v_mov_b64_e32 v[32:33], v[48:49]
	v_mov_b64_e32 v[34:35], v[50:51]
	v_mov_b64_e32 v[36:37], v[52:53]
	v_mov_b64_e32 v[38:39], v[54:55]
	s_branch .LBB0_1531
.Lcb_done:
.LBB0_1532:
	s_waitcnt vmcnt(0)
	s_waitcnt lgkmcnt(0)
	s_barrier
	s_nop 0
	v_mbcnt_lo_u32_b32 v0, -1, v14
	v_mbcnt_hi_u32_b32 v0, -1, v0
	v_cmp_eq_u32_e32 vcc, s3, v0
	s_and_saveexec_b64 s[4:5], vcc
	s_cbranch_execz .LBB0_1584
	s_add_i32 s6, 0, 0x23e00
	v_mov_b32_e32 v0, s6
	s_waitcnt vmcnt(0) expcnt(0) lgkmcnt(0)
	ds_read_b32 v2, v0
	s_add_i32 s6, 0, 0x23e04
	v_mov_b32_e32 v0, s6
	ds_read_b32 v0, v0
	s_waitcnt lgkmcnt(1)
	v_cmp_ne_u32_e32 vcc, 0, v2
	s_cbranch_vccnz .LBB0_1548
	s_add_u32 s6, s14, 0x1000
	s_addc_u32 s7, s15, 0
	s_add_u32 s8, s14, 0x1100
	s_addc_u32 s9, s15, 0
	s_add_u32 s10, s14, 0x1200
	s_addc_u32 s11, s15, 0
	s_mul_i32 s26, s59, s78
	s_add_u32 s18, s14, 0x1300
	s_mul_i32 s26, s26, s58
	s_addc_u32 s19, s15, 0
	s_mov_b32 s27, 1
	v_mov_b32_e32 v16, 0
	s_branch .LBB0_1536

.LBB0_1899:
	s_or_b64 exec, exec, s[2:3]
	s_waitcnt lgkmcnt(0)
	v_mov_b32_e32 v0, 0
	s_barrier
	v_mov_b32_e32 v1, 0
	v_mbcnt_lo_u32_b32 v0, -1, v0
	v_mbcnt_hi_u32_b32 v0, -1, v0
	v_add_u32_e32 v0, s33, v0
	s_nop 0
	v_readfirstlane_b32 s2, v0
	s_ashr_i32 s2, s2, 6
	s_add_i32 s8, s2, s76
	s_cmpk_gt_i32 s8, 0x3fff
	s_cbranch_scc1 .LBB0_1902
	s_load_dwordx2 s[0:1], s[0:1], 0x20
	s_ashr_i32 s3, s2, 31
	s_ashr_i32 s4, s76, 31
	s_add_u32 s6, s2, s76
	s_addc_u32 s7, s3, s4
	v_and_b32_e32 v4, 63, v0
	s_lshl_b64 s[4:5], s[6:7], 11
	v_lshlrev_b32_e32 v0, 4, v4
	s_ashr_i32 s35, s34, 31
	v_lshl_or_b32 v4, v4, 3, s4
	v_mov_b32_e32 v5, s5
	s_mov_b64 s[4:5], 0x3800400
	s_waitcnt lgkmcnt(0)
	v_lshl_add_u64 v[2:3], s[0:1], 0, v[0:1]
	s_lshl_b64 s[0:1], s[6:7], 6
	s_lshl_b64 s[2:3], s[34:35], 6
	v_lshl_add_u64 v[4:5], v[4:5], 0, s[4:5]
	s_lshl_b64 s[4:5], s[34:35], 11
	s_lshl_b64 s[6:7], s[6:7], 12
	v_readlane_b32 s10, v254, 0
	v_readlane_b32 s11, v254, 1
	s_add_u32 s6, s10, s6
	s_addc_u32 s7, s11, s7
	v_lshl_add_u64 v[6:7], s[6:7], 0, v[0:1]
	s_mov_b64 s[6:7], 0xc00
	v_lshl_add_u64 v[6:7], v[6:7], 0, s[6:7]
	s_lshl_b64 s[6:7], s[34:35], 12
	v_mov_b32_e32 v0, 0x500000
	v_mov_b32_e32 v8, 0x358637bd
	s_mov_b32 s9, 0x800000
	global_load_dwordx4 v[40:43], v[2:3], off
	global_load_dwordx4 v[44:47], v[2:3], off offset:1024
	global_load_dwordx4 v[48:51], v[2:3], off offset:2048
	global_load_dwordx4 v[52:55], v[2:3], off offset:3072
	s_waitcnt vmcnt(0)
.LBB0_1901:
	s_add_u32 s10, s14, s0
	s_addc_u32 s11, s15, s1
	v_lshl_add_u64 v[30:31], s[14:15], 0, v[4:5]
	global_load_dwordx4 v[10:13], v0, s[10:11]
	global_load_dwordx2 v[32:33], v[30:31], off offset:-1024
	s_add_u32 s10, s10, 0x500000
	s_addc_u32 s11, s11, 0
	global_load_dwordx4 v[14:17], v1, s[10:11] offset:16
	global_load_dwordx4 v[18:21], v1, s[10:11] offset:32
	global_load_dwordx4 v[22:25], v1, s[10:11] offset:48
	global_load_dwordx2 v[36:37], v[30:31], off offset:-512
	global_load_dwordx2 v[38:39], v[30:31], off
	global_load_dwordx2 v[56:57], v[30:31], off offset:512
	s_add_i32 s8, s8, s34
	s_add_u32 s0, s0, s2
	s_addc_u32 s1, s1, s3
	v_lshl_add_u64 v[4:5], v[4:5], 0, s[4:5]
	s_cmpk_gt_i32 s8, 0x3fff
	s_waitcnt vmcnt(7)
	v_mov_b32_e32 v34, v11
	v_mov_b32_e32 v35, v12
	v_mov_b32_e32 v11, v13
	v_pk_add_f32 v[10:11], v[34:35], v[10:11]
	s_waitcnt vmcnt(6)
	v_lshlrev_b32_e32 v12, 16, v32
	v_add_f32_e32 v9, v10, v11
	s_waitcnt vmcnt(5)
	v_mov_b32_e32 v10, v15
	v_mov_b32_e32 v11, v16
	v_mov_b32_e32 v15, v17
	v_pk_add_f32 v[10:11], v[10:11], v[14:15]
	s_waitcnt vmcnt(4)
	v_add_f32_e32 v16, v18, v19
	v_pk_add_f32 v[10:11], v[10:11], v[10:11] op_sel:[0,1] op_sel_hi:[1,0]
	v_add_f32_e32 v18, v20, v21
	s_waitcnt vmcnt(3)
	v_mov_b32_e32 v21, v22
	v_mov_b32_e32 v17, v24
	v_mov_b32_e32 v19, v25
	v_add_f32_e32 v20, 0, v9
	v_mov_b32_e32 v11, v23
	v_pk_add_f32 v[14:15], v[16:17], v[18:19]
	v_pk_add_f32 v[10:11], v[20:21], v[10:11]
	v_and_b32_e32 v13, 0xffff0000, v32
	v_pk_add_f32 v[10:11], v[10:11], v[14:15]
	v_lshlrev_b32_e32 v32, 16, v33
	v_add_f32_e32 v9, v10, v11
	v_fmamk_f32 v9, v9, 0x3a800000, v8
	v_mul_f32_e32 v10, 0x4b800000, v9
	v_cmp_gt_f32_e32 vcc, s9, v9
	v_and_b32_e32 v33, 0xffff0000, v33
	s_nop 0
	v_cndmask_b32_e32 v9, v9, v10, vcc
	v_rsq_f32_e32 v9, v9
	s_nop 0
	v_mul_f32_e32 v10, 0x45800000, v9
	v_cndmask_b32_e32 v14, v9, v10, vcc
	v_pk_mul_f32 v[10:11], v[14:15], v[12:13] op_sel_hi:[0,1]
	v_pk_mul_f32 v[12:13], v[14:15], v[32:33] op_sel_hi:[0,1]
	v_pk_mul_f32 v[12:13], v[42:43], v[12:13]
	v_pk_mul_f32 v[10:11], v[40:41], v[10:11]
	global_store_dwordx4 v[6:7], v[10:13], off offset:-3072
	s_waitcnt vmcnt(3)
	v_mov_b64_e32 v[16:17], v[36:37]
	v_mov_b64_e32 v[10:11], v[44:45]
	v_mov_b64_e32 v[12:13], v[46:47]
	v_lshlrev_b32_e32 v18, 16, v16
	v_and_b32_e32 v19, 0xffff0000, v16
	v_lshlrev_b32_e32 v16, 16, v17
	v_and_b32_e32 v17, 0xffff0000, v17
	v_pk_mul_f32 v[18:19], v[14:15], v[18:19] op_sel_hi:[0,1]
	v_pk_mul_f32 v[16:17], v[14:15], v[16:17] op_sel_hi:[0,1]
	v_pk_mul_f32 v[12:13], v[12:13], v[16:17]
	v_pk_mul_f32 v[10:11], v[10:11], v[18:19]
	global_store_dwordx4 v[6:7], v[10:13], off offset:-2048
	s_waitcnt vmcnt(3)
	v_mov_b64_e32 v[16:17], v[38:39]
	v_mov_b64_e32 v[10:11], v[48:49]
	v_mov_b64_e32 v[12:13], v[50:51]
	v_lshlrev_b32_e32 v18, 16, v16
	v_and_b32_e32 v19, 0xffff0000, v16
	v_lshlrev_b32_e32 v16, 16, v17
	v_and_b32_e32 v17, 0xffff0000, v17
	v_pk_mul_f32 v[18:19], v[14:15], v[18:19] op_sel_hi:[0,1]
	v_pk_mul_f32 v[16:17], v[14:15], v[16:17] op_sel_hi:[0,1]
	v_pk_mul_f32 v[12:13], v[12:13], v[16:17]
	v_pk_mul_f32 v[10:11], v[10:11], v[18:19]
	global_store_dwordx4 v[6:7], v[10:13], off offset:-1024
	s_waitcnt vmcnt(3)
	v_mov_b64_e32 v[16:17], v[56:57]
	v_mov_b64_e32 v[10:11], v[52:53]
	v_mov_b64_e32 v[12:13], v[54:55]
	v_lshlrev_b32_e32 v18, 16, v16
	v_and_b32_e32 v19, 0xffff0000, v16
	v_lshlrev_b32_e32 v16, 16, v17
	v_and_b32_e32 v17, 0xffff0000, v17
	v_pk_mul_f32 v[18:19], v[14:15], v[18:19] op_sel_hi:[0,1]
	v_pk_mul_f32 v[14:15], v[14:15], v[16:17] op_sel_hi:[0,1]
	v_pk_mul_f32 v[12:13], v[12:13], v[14:15]
	v_pk_mul_f32 v[10:11], v[10:11], v[18:19]
	global_store_dwordx4 v[6:7], v[10:13], off
	v_lshl_add_u64 v[6:7], v[6:7], 0, s[6:7]
	s_cbranch_scc0 .LBB0_1901
